# phase 0: p->bf16 loads batched 8 trips deep; x row pass gain vectors loaded once instead of per row behind vmcnt(0)
# speedup vs baseline: 1.0189x; 1.0030x over previous
.Lp2b_batch:
	s_mul_i32 vcc_lo, s96, 7
	s_add_i32 vcc_lo, vcc_lo, s0
	s_cmpk_lt_i32 vcc_lo, 0x1000
	s_cbranch_scc0 .Lp2b_rem
	global_load_dwordx4 v[16:19], v[4:5], off offset:-16
	global_load_dwordx4 v[20:23], v[4:5], off
	v_lshl_add_u64 v[4:5], v[4:5], 0, s[4:5]
	global_load_dwordx4 v[24:27], v[4:5], off offset:-16
	global_load_dwordx4 v[28:31], v[4:5], off
	v_lshl_add_u64 v[4:5], v[4:5], 0, s[4:5]
	global_load_dwordx4 v[32:35], v[4:5], off offset:-16
	global_load_dwordx4 v[36:39], v[4:5], off
	v_lshl_add_u64 v[4:5], v[4:5], 0, s[4:5]
	global_load_dwordx4 v[40:43], v[4:5], off offset:-16
	global_load_dwordx4 v[44:47], v[4:5], off
	v_lshl_add_u64 v[4:5], v[4:5], 0, s[4:5]
	global_load_dwordx4 v[48:51], v[4:5], off offset:-16
	global_load_dwordx4 v[52:55], v[4:5], off
	v_lshl_add_u64 v[4:5], v[4:5], 0, s[4:5]
	global_load_dwordx4 v[56:59], v[4:5], off offset:-16
	global_load_dwordx4 v[60:63], v[4:5], off
	v_lshl_add_u64 v[4:5], v[4:5], 0, s[4:5]
	global_load_dwordx4 v[64:67], v[4:5], off offset:-16
	global_load_dwordx4 v[68:71], v[4:5], off
	v_lshl_add_u64 v[4:5], v[4:5], 0, s[4:5]
	global_load_dwordx4 v[72:75], v[4:5], off offset:-16
	global_load_dwordx4 v[76:79], v[4:5], off
	v_lshl_add_u64 v[4:5], v[4:5], 0, s[4:5]
	s_waitcnt vmcnt(14)
	v_cvt_pk_bf16_f32 v16, v16, v17
	v_cvt_pk_bf16_f32 v17, v18, v19
	v_cvt_pk_bf16_f32 v18, v20, v21
	v_cvt_pk_bf16_f32 v19, v22, v23
	global_store_dwordx4 v[2:3], v[16:19], off
	v_lshl_add_u64 v[2:3], v[2:3], 0, s[2:3]
	s_waitcnt vmcnt(13)
	v_cvt_pk_bf16_f32 v24, v24, v25
	v_cvt_pk_bf16_f32 v25, v26, v27
	v_cvt_pk_bf16_f32 v26, v28, v29
	v_cvt_pk_bf16_f32 v27, v30, v31
	global_store_dwordx4 v[2:3], v[24:27], off
	v_lshl_add_u64 v[2:3], v[2:3], 0, s[2:3]
	s_waitcnt vmcnt(12)
	v_cvt_pk_bf16_f32 v32, v32, v33
	v_cvt_pk_bf16_f32 v33, v34, v35
	v_cvt_pk_bf16_f32 v34, v36, v37
	v_cvt_pk_bf16_f32 v35, v38, v39
	global_store_dwordx4 v[2:3], v[32:35], off
	v_lshl_add_u64 v[2:3], v[2:3], 0, s[2:3]
	s_waitcnt vmcnt(11)
	v_cvt_pk_bf16_f32 v40, v40, v41
	v_cvt_pk_bf16_f32 v41, v42, v43
	v_cvt_pk_bf16_f32 v42, v44, v45
	v_cvt_pk_bf16_f32 v43, v46, v47
	global_store_dwordx4 v[2:3], v[40:43], off
	v_lshl_add_u64 v[2:3], v[2:3], 0, s[2:3]
	s_waitcnt vmcnt(10)
	v_cvt_pk_bf16_f32 v48, v48, v49
	v_cvt_pk_bf16_f32 v49, v50, v51
	v_cvt_pk_bf16_f32 v50, v52, v53
	v_cvt_pk_bf16_f32 v51, v54, v55
	global_store_dwordx4 v[2:3], v[48:51], off
	v_lshl_add_u64 v[2:3], v[2:3], 0, s[2:3]
	s_waitcnt vmcnt(9)
	v_cvt_pk_bf16_f32 v56, v56, v57
	v_cvt_pk_bf16_f32 v57, v58, v59
	v_cvt_pk_bf16_f32 v58, v60, v61
	v_cvt_pk_bf16_f32 v59, v62, v63
	global_store_dwordx4 v[2:3], v[56:59], off
	v_lshl_add_u64 v[2:3], v[2:3], 0, s[2:3]
	s_waitcnt vmcnt(8)
	v_cvt_pk_bf16_f32 v64, v64, v65
	v_cvt_pk_bf16_f32 v65, v66, v67
	v_cvt_pk_bf16_f32 v66, v68, v69
	v_cvt_pk_bf16_f32 v67, v70, v71
	global_store_dwordx4 v[2:3], v[64:67], off
	v_lshl_add_u64 v[2:3], v[2:3], 0, s[2:3]
	s_waitcnt vmcnt(7)
	v_cvt_pk_bf16_f32 v72, v72, v73
	v_cvt_pk_bf16_f32 v73, v74, v75
	v_cvt_pk_bf16_f32 v74, v76, v77
	v_cvt_pk_bf16_f32 v75, v78, v79
	global_store_dwordx4 v[2:3], v[72:75], off
	v_lshl_add_u64 v[2:3], v[2:3], 0, s[2:3]
	s_lshl_b32 vcc_lo, s96, 3
	s_add_i32 s0, s0, vcc_lo
	s_branch .Lp2b_batch
.Lp2b_rem:
	s_cmpk_lt_i32 s0, 0x1000
	s_cbranch_scc0 .Lp2b_done

.Lp2b_done:
	v_ashrrev_i32_e32 v0, 6, v0
	v_readlane_b32 s2, v254, 49
	v_add_u32_e32 v20, s69, v0
	s_mov_b32 s0, s2
	v_readlane_b32 s3, v254, 50
	v_readlane_b32 s2, v254, 6
	v_readlane_b32 s3, v254, 7
	v_mov_b32_e32 v32, 1.0
	v_mov_b32_e32 v33, 1.0
	v_mov_b32_e32 v34, 1.0
	v_mov_b32_e32 v35, 1.0
	v_mov_b32_e32 v36, 1.0
	v_mov_b32_e32 v37, 1.0
	v_mov_b32_e32 v38, 1.0
	v_mov_b32_e32 v39, 1.0
	v_mov_b32_e32 v40, 1.0
	v_mov_b32_e32 v41, 1.0
	v_mov_b32_e32 v42, 1.0
	v_mov_b32_e32 v43, 1.0
	v_mov_b32_e32 v44, 1.0
	v_mov_b32_e32 v45, 1.0
	v_mov_b32_e32 v46, 1.0
	v_mov_b32_e32 v47, 1.0
	v_and_b32_e32 v30, 63, v204
	v_lshlrev_b32_e32 v30, 4, v30
	s_andn2_b64 vcc, exec, s[2:3]
	s_cbranch_vccnz .Lrp0_nogain
	v_readlane_b32 s8, v252, 12
	v_readlane_b32 s9, v252, 13
	s_nop 4
	global_load_dwordx4 v[32:35], v30, s[8:9]
	global_load_dwordx4 v[36:39], v30, s[8:9] offset:1024
	global_load_dwordx4 v[40:43], v30, s[8:9] offset:2048
	global_load_dwordx4 v[44:47], v30, s[8:9] offset:3072
.Lrp0_nogain:
	s_waitcnt vmcnt(0)
	s_branch .LBB0_637
.LBB0_635:
	v_mov_b32_e32 v4, v44
	v_mov_b32_e32 v5, v45
	v_mov_b32_e32 v6, v46
	v_mov_b32_e32 v7, v47
.LBB0_636:
	v_pk_mul_f32 v[0:1], v[0:1], v[24:25]
	v_pk_mul_f32 v[2:3], v[2:3], v[24:25]
	v_pk_mul_f32 v[0:1], v[0:1], v[4:5]
	v_pk_mul_f32 v[2:3], v[2:3], v[6:7]
	s_add_i32 s0, s0, s96
	v_cvt_pk_bf16_f32 v0, v0, v1
	v_cvt_pk_bf16_f32 v1, v2, v3
	s_cmpk_gt_i32 s0, 0xfff
	v_add_u32_e32 v20, s70, v20
	global_store_dwordx2 v[22:23], v[0:1], off offset:1536
	s_cbranch_scc1 .LBB0_24

.LBB0_642:
	v_readlane_b32 s2, v253, 2
	v_readlane_b32 s3, v253, 3
	v_lshlrev_b32_e32 v188, 1, v19
	s_waitcnt vmcnt(0)
	v_cvt_pk_bf16_f32 v28, v12, v13
	v_lshl_add_u64 v[26:27], s[2:3], 0, v[22:23]
	v_lshl_add_u64 v[26:27], v[26:27], 0, v[188:189]
	v_cvt_pk_bf16_f32 v29, v14, v15
	global_store_dwordx2 v[26:27], v[28:29], off
	v_cvt_pk_bf16_f32 v28, v8, v9
	v_cvt_pk_bf16_f32 v29, v10, v11
	global_store_dwordx2 v[26:27], v[28:29], off offset:512
	v_cvt_pk_bf16_f32 v28, v4, v5
	v_cvt_pk_bf16_f32 v29, v6, v7
	v_readlane_b32 s8, v252, 12
	global_store_dwordx2 v[26:27], v[28:29], off offset:1024
	v_cvt_pk_bf16_f32 v28, v0, v1
	v_cvt_pk_bf16_f32 v29, v2, v3
	v_mov_b32_e32 v17, v189
	v_readlane_b32 s9, v252, 13
	global_store_dwordx2 v[26:27], v[28:29], off offset:1536
	s_and_b64 vcc, exec, s[4:5]
	v_lshl_add_u64 v[26:27], s[8:9], 0, v[16:17]
	v_mov_b32_e32 v19, 1.0
	v_mov_b32_e32 v16, 1.0
	v_mov_b32_e32 v17, 1.0
	v_readlane_b32 s10, v252, 14
	v_readlane_b32 s11, v252, 15
	v_readlane_b32 s12, v252, 16
	v_readlane_b32 s13, v252, 17
	v_readlane_b32 s14, v252, 18
	v_readlane_b32 s15, v252, 19
	v_readlane_b32 s16, v252, 20
	v_readlane_b32 s17, v252, 21
	v_readlane_b32 s18, v252, 22
	v_readlane_b32 s19, v252, 23
	v_readlane_b32 s20, v252, 24
	v_readlane_b32 s21, v252, 25
	v_readlane_b32 s22, v252, 26
	v_readlane_b32 s23, v252, 27
	s_cbranch_vccnz .LBB0_644
	v_mov_b32_e32 v16, v32
	v_mov_b32_e32 v17, v33
	v_mov_b32_e32 v18, v34
	v_mov_b32_e32 v19, v35
.LBB0_644:
	v_readlane_b32 s2, v254, 32
	v_readlane_b32 s3, v254, 33
	v_pk_mul_f32 v[12:13], v[12:13], v[24:25] op_sel_hi:[1,0]
	v_pk_mul_f32 v[14:15], v[14:15], v[24:25] op_sel_hi:[1,0]
	v_lshl_add_u64 v[22:23], s[2:3], 0, v[22:23]
	v_pk_mul_f32 v[12:13], v[12:13], v[16:17]
	v_pk_mul_f32 v[14:15], v[14:15], v[18:19]
	v_lshl_add_u64 v[22:23], v[22:23], 0, v[188:189]
	v_cvt_pk_bf16_f32 v12, v12, v13
	v_cvt_pk_bf16_f32 v13, v14, v15
	global_store_dwordx2 v[22:23], v[12:13], off
	v_mov_b32_e32 v12, 1.0
	s_and_b64 vcc, exec, s[4:5]
	v_mov_b32_e32 v16, 1.0
	v_mov_b32_e32 v17, 1.0
	v_mov_b32_e32 v14, 1.0
	v_mov_b32_e32 v15, 1.0
	s_cbranch_vccnz .LBB0_646
	v_mov_b32_e32 v14, v36
	v_mov_b32_e32 v15, v37
	v_mov_b32_e32 v16, v38
	v_mov_b32_e32 v17, v39
.LBB0_646:
	v_mov_b32_e32 v25, v24
	v_pk_mul_f32 v[8:9], v[8:9], v[24:25]
	v_pk_mul_f32 v[10:11], v[10:11], v[24:25]
	v_pk_mul_f32 v[8:9], v[8:9], v[14:15]
	v_pk_mul_f32 v[10:11], v[10:11], v[16:17]
	v_cvt_pk_bf16_f32 v8, v8, v9
	v_cvt_pk_bf16_f32 v9, v10, v11
	s_and_b64 vcc, exec, s[4:5]
	v_mov_b32_e32 v13, 1.0
	v_mov_b32_e32 v10, 1.0
	v_mov_b32_e32 v11, 1.0
	global_store_dwordx2 v[22:23], v[8:9], off offset:512
	s_cbranch_vccnz .LBB0_648
	v_mov_b32_e32 v10, v40
	v_mov_b32_e32 v11, v41
	v_mov_b32_e32 v12, v42
	v_mov_b32_e32 v13, v43
.LBB0_648:
	v_pk_mul_f32 v[4:5], v[4:5], v[24:25]
	v_pk_mul_f32 v[6:7], v[6:7], v[24:25]
	v_pk_mul_f32 v[4:5], v[4:5], v[10:11]
	v_pk_mul_f32 v[6:7], v[6:7], v[12:13]
	v_cvt_pk_bf16_f32 v4, v4, v5
	v_cvt_pk_bf16_f32 v5, v6, v7
	s_and_b64 vcc, exec, s[4:5]
	global_store_dwordx2 v[22:23], v[4:5], off offset:1024
	s_cbranch_vccz .LBB0_635
	v_mov_b32_e32 v6, 1.0
	v_mov_b32_e32 v7, v6
	v_mov_b32_e32 v4, v6
	v_mov_b32_e32 v5, v6
	s_branch .LBB0_636
